# attention row-max cross-half exchange: ds_bpermute + lgkmcnt wait replaced by v_permlane32_swap_b32 (6 loops)
# speedup vs baseline: 1.0107x; 1.0002x over previous
.LBB0_323:
	s_and_saveexec_b64 s[72:73], s[6:7]
	s_cbranch_execz .LBB0_310
	ds_read_b128 v[220:223], v245
	ds_read_b128 v[224:227], v245 offset:32
	ds_read_b128 v[2:5], v245 offset:64
	ds_read_b128 v[6:9], v245 offset:96
	s_waitcnt lgkmcnt(3)
	v_mfma_f32_32x32x16_bf16 v[96:111], v[220:223], v[172:175], 0
	ds_read_b128 v[220:223], v245 offset:128
	s_waitcnt lgkmcnt(3)
	v_mfma_f32_32x32x16_bf16 v[96:111], v[224:227], v[168:171], v[96:111]
	ds_read_b128 v[224:227], v245 offset:160
	s_waitcnt lgkmcnt(3)
	v_mfma_f32_32x32x16_bf16 v[96:111], v[2:5], v[164:167], v[96:111]
	ds_read_b128 v[2:5], v245 offset:192
	s_waitcnt lgkmcnt(3)
	v_mfma_f32_32x32x16_bf16 v[96:111], v[6:9], v[160:163], v[96:111]
	ds_read_b128 v[6:9], v245 offset:224
	s_waitcnt lgkmcnt(3)
	v_mfma_f32_32x32x16_bf16 v[96:111], v[220:223], v[156:159], v[96:111]
	ds_read_b128 v[220:223], v245 offset:256
	s_waitcnt lgkmcnt(3)
	v_mfma_f32_32x32x16_bf16 v[96:111], v[224:227], v[152:155], v[96:111]
	ds_read_b128 v[224:227], v245 offset:288
	s_waitcnt lgkmcnt(3)
	v_mfma_f32_32x32x16_bf16 v[96:111], v[2:5], v[148:151], v[96:111]
	ds_read_b128 v[2:5], v245 offset:320
	s_waitcnt lgkmcnt(3)
	v_mfma_f32_32x32x16_bf16 v[96:111], v[6:9], v[144:147], v[96:111]
	ds_read_b128 v[6:9], v245 offset:352
	s_waitcnt lgkmcnt(3)
	v_mfma_f32_32x32x16_bf16 v[96:111], v[220:223], v[140:143], v[96:111]
	ds_read_b128 v[220:223], v245 offset:384
	s_waitcnt lgkmcnt(3)
	v_mfma_f32_32x32x16_bf16 v[96:111], v[224:227], v[136:139], v[96:111]
	ds_read_b128 v[224:227], v245 offset:416
	s_waitcnt lgkmcnt(3)
	v_mfma_f32_32x32x16_bf16 v[96:111], v[2:5], v[132:135], v[96:111]
	ds_read_b128 v[2:5], v245 offset:448
	s_waitcnt lgkmcnt(3)
	v_mfma_f32_32x32x16_bf16 v[96:111], v[6:9], v[128:131], v[96:111]
	ds_read_b128 v[6:9], v245 offset:480
	s_waitcnt lgkmcnt(3)
	v_mfma_f32_32x32x16_bf16 v[96:111], v[220:223], v[124:127], v[96:111]
	ds_read_b128 v[220:223], v245 offset:16896
	s_waitcnt lgkmcnt(3)
	v_mfma_f32_32x32x16_bf16 v[96:111], v[224:227], v[120:123], v[96:111]
	ds_read_b128 v[224:227], v245 offset:16928
	s_waitcnt lgkmcnt(3)
	v_mfma_f32_32x32x16_bf16 v[96:111], v[2:5], v[116:119], v[96:111]
	ds_read_b128 v[2:5], v245 offset:16960
	s_waitcnt lgkmcnt(3)
	v_mfma_f32_32x32x16_bf16 v[96:111], v[6:9], v[112:115], v[96:111]
	ds_read_b128 v[6:9], v245 offset:16992
	s_waitcnt lgkmcnt(3)
	v_mfma_f32_32x32x16_bf16 v[80:95], v[220:223], v[172:175], 0
	ds_read_b128 v[220:223], v245 offset:17024
	s_waitcnt lgkmcnt(3)
	v_mfma_f32_32x32x16_bf16 v[80:95], v[224:227], v[168:171], v[80:95]
	ds_read_b128 v[224:227], v245 offset:17056
	s_waitcnt lgkmcnt(3)
	v_mfma_f32_32x32x16_bf16 v[80:95], v[2:5], v[164:167], v[80:95]
	ds_read_b128 v[2:5], v245 offset:17088
	s_waitcnt lgkmcnt(3)
	v_mfma_f32_32x32x16_bf16 v[80:95], v[6:9], v[160:163], v[80:95]
	ds_read_b128 v[6:9], v245 offset:17120
	s_waitcnt lgkmcnt(3)
	v_mfma_f32_32x32x16_bf16 v[80:95], v[220:223], v[156:159], v[80:95]
	ds_read_b128 v[220:223], v245 offset:17152
	s_waitcnt lgkmcnt(3)
	v_mfma_f32_32x32x16_bf16 v[80:95], v[224:227], v[152:155], v[80:95]
	ds_read_b128 v[224:227], v245 offset:17184
	s_waitcnt lgkmcnt(3)
	v_mfma_f32_32x32x16_bf16 v[80:95], v[2:5], v[148:151], v[80:95]
	ds_read_b128 v[2:5], v245 offset:17216
	s_waitcnt lgkmcnt(3)
	v_mfma_f32_32x32x16_bf16 v[80:95], v[6:9], v[144:147], v[80:95]
	ds_read_b128 v[6:9], v245 offset:17248
	s_waitcnt lgkmcnt(3)
	v_mfma_f32_32x32x16_bf16 v[80:95], v[220:223], v[140:143], v[80:95]
	ds_read_b128 v[220:223], v245 offset:17280
	s_waitcnt lgkmcnt(3)
	v_mfma_f32_32x32x16_bf16 v[80:95], v[224:227], v[136:139], v[80:95]
	ds_read_b128 v[224:227], v245 offset:17312
	s_waitcnt lgkmcnt(3)
	v_mfma_f32_32x32x16_bf16 v[80:95], v[2:5], v[132:135], v[80:95]
	ds_read_b128 v[2:5], v245 offset:17344
	s_waitcnt lgkmcnt(3)
	v_mfma_f32_32x32x16_bf16 v[80:95], v[6:9], v[128:131], v[80:95]
	ds_read_b128 v[6:9], v245 offset:17376
	s_waitcnt lgkmcnt(3)
	v_mfma_f32_32x32x16_bf16 v[80:95], v[220:223], v[124:127], v[80:95]
	s_waitcnt lgkmcnt(2)
	v_mfma_f32_32x32x16_bf16 v[80:95], v[224:227], v[120:123], v[80:95]
	s_waitcnt lgkmcnt(1)
	v_mfma_f32_32x32x16_bf16 v[80:95], v[2:5], v[116:119], v[80:95]
	s_waitcnt lgkmcnt(0)
	v_mfma_f32_32x32x16_bf16 v[80:95], v[6:9], v[112:115], v[80:95]
	v_max_f32_e32 v0, v97, v97
	v_max_f32_e32 v10, v96, v96
	v_max_f32_e32 v0, v10, v0
	v_max3_f32 v0, v0, v98, v99
	v_max3_f32 v0, v0, v100, v101
	v_max3_f32 v0, v0, v102, v103
	v_max3_f32 v0, v0, v104, v105
	v_max3_f32 v0, v0, v106, v107
	v_max3_f32 v0, v0, v108, v109
	v_max3_f32 v0, v0, v110, v111
	v_and_b32_e32 v3, 64, v218
	v_xor_b32_e32 v2, 32, v218
	v_add_u32_e32 v3, 64, v3
	v_cmp_lt_i32_e32 vcc, v2, v3
	s_nop 1
	v_cndmask_b32_e32 v2, v218, v2, vcc
	v_lshlrev_b32_e32 v2, 2, v2
	s_nop 10
	v_max3_f32 v0, v0, v80, v81
	v_max3_f32 v0, v0, v82, v83
	v_max3_f32 v0, v0, v84, v85
	v_max3_f32 v0, v0, v86, v87
	v_max3_f32 v0, v0, v88, v89
	v_max3_f32 v0, v0, v90, v91
	v_max3_f32 v0, v0, v92, v93
	v_max3_f32 v0, v0, v94, v95
	v_mov_b32_e32 v2, v0
	s_nop 1
	v_permlane32_swap_b32_e32 v2, v0
	s_nop 1
	v_max3_f32 v0, v236, v0, v2
	v_sub_f32 v4, v97, v0
	v_sub_f32 v3, v96, v0
	v_sub_f32 v5, v100, v0
	v_sub_f32_e32 v2, v236, v0
	v_exp_f32_e32 v8, v4
	v_sub_f32 v4, v98, v0
	v_exp_f32_e32 v3, v3
	v_exp_f32_e32 v9, v4
	v_sub_f32 v4, v99, v0
	v_exp_f32_e32 v11, v5
	v_exp_f32_e32 v10, v4
	v_add_f32 v4, v1, v3
	v_sub_f32 v5, v101, v0
	v_exp_f32_e32 v2, v2
	v_add_f32 v4, v4, v8
	v_exp_f32_e32 v12, v5
	v_add_f32 v4, v4, v9
	v_sub_f32 v5, v102, v0
	v_cvt_pk_bf16_f32 v8, v3, v8
	v_add_f32 v4, v4, v10
	v_exp_f32_e32 v13, v5
	v_add_f32 v4, v4, v11
	v_sub_f32 v5, v103, v0
	v_add_u32_e32 v3, 0x9000, v219
	v_add_f32 v4, v4, v12
	v_exp_f32_e32 v14, v5
	v_add_f32 v4, v4, v13
	v_cvt_pk_bf16_f32 v9, v9, v10
	v_add_f32 v96, v4, v14
	v_sub_f32 v4, v104, v0
	v_add_u32_e32 v104, 0x8000, v219
	v_exp_f32_e32 v97, v4
	v_sub_f32 v4, v105, v0
	v_cvt_pk_bf16_f32 v10, v11, v12
	v_exp_f32_e32 v98, v4
	v_sub_f32 v4, v106, v0
	v_cvt_pk_bf16_f32 v11, v13, v14
	v_exp_f32_e32 v99, v4
	v_sub_f32 v4, v107, v0
	ds_read2_b64 v[12:15], v3 offset0:160 offset1:162
	v_exp_f32_e32 v100, v4
	v_sub_f32 v4, v108, v0
	v_pk_mul_f32 v[64:65], v[64:65], v[2:3] op_sel_hi:[1,0]
	v_pk_mul_f32 v[66:67], v[66:67], v[2:3] op_sel_hi:[1,0]
	v_pk_mul_f32 v[68:69], v[68:69], v[2:3] op_sel_hi:[1,0]
	s_nop 0
	v_exp_f32_e32 v101, v4
	v_sub_f32 v4, v109, v0
	v_pk_mul_f32 v[70:71], v[70:71], v[2:3] op_sel_hi:[1,0]
	v_pk_mul_f32 v[72:73], v[72:73], v[2:3] op_sel_hi:[1,0]
	s_nop 0
	v_exp_f32_e32 v102, v4
	v_sub_f32 v4, v110, v0
	v_pk_mul_f32 v[74:75], v[74:75], v[2:3] op_sel_hi:[1,0]
	v_pk_mul_f32 v[76:77], v[76:77], v[2:3] op_sel_hi:[1,0]
	v_pk_mul_f32 v[78:79], v[78:79], v[2:3] op_sel_hi:[1,0]
	s_nop 0
	v_exp_f32_e32 v103, v4
	ds_read2_b64 v[4:7], v104 offset0:128 offset1:130
	v_add_u32_e32 v105, 0xa000, v219
	s_waitcnt lgkmcnt(0)
	v_mfma_f32_32x32x16_bf16 v[64:79], v[4:7], v[8:11], v[64:79]
	ds_read2_b64 v[4:7], v105 offset0:192 offset1:194
	v_pk_mul_f32 v[48:49], v[48:49], v[2:3] op_sel_hi:[1,0]
	v_pk_mul_f32 v[50:51], v[50:51], v[2:3] op_sel_hi:[1,0]
	v_pk_mul_f32 v[52:53], v[52:53], v[2:3] op_sel_hi:[1,0]
	v_pk_mul_f32 v[54:55], v[54:55], v[2:3] op_sel_hi:[1,0]
	v_pk_mul_f32 v[56:57], v[56:57], v[2:3] op_sel_hi:[1,0]
	v_pk_mul_f32 v[58:59], v[58:59], v[2:3] op_sel_hi:[1,0]
	v_pk_mul_f32 v[60:61], v[60:61], v[2:3] op_sel_hi:[1,0]
	v_pk_mul_f32 v[62:63], v[62:63], v[2:3] op_sel_hi:[1,0]
	v_add_u32_e32 v106, 0xb000, v219
	v_mfma_f32_32x32x16_bf16 v[48:63], v[12:15], v[8:11], v[48:63]
	ds_read2_b64 v[12:15], v106 offset0:224 offset1:226
	v_pk_mul_f32 v[32:33], v[32:33], v[2:3] op_sel_hi:[1,0]
	v_pk_mul_f32 v[34:35], v[34:35], v[2:3] op_sel_hi:[1,0]
	v_pk_mul_f32 v[36:37], v[36:37], v[2:3] op_sel_hi:[1,0]
	v_pk_mul_f32 v[38:39], v[38:39], v[2:3] op_sel_hi:[1,0]
	v_pk_mul_f32 v[40:41], v[40:41], v[2:3] op_sel_hi:[1,0]
	v_pk_mul_f32 v[42:43], v[42:43], v[2:3] op_sel_hi:[1,0]
	v_pk_mul_f32 v[44:45], v[44:45], v[2:3] op_sel_hi:[1,0]
	v_pk_mul_f32 v[46:47], v[46:47], v[2:3] op_sel_hi:[1,0]
	v_pk_mul_f32 v[16:17], v[16:17], v[2:3] op_sel_hi:[1,0]
	v_pk_mul_f32 v[18:19], v[18:19], v[2:3] op_sel_hi:[1,0]
	v_pk_mul_f32 v[20:21], v[20:21], v[2:3] op_sel_hi:[1,0]
	s_waitcnt lgkmcnt(1)
	v_mfma_f32_32x32x16_bf16 v[32:47], v[4:7], v[8:11], v[32:47]
	ds_read2_b64 v[4:7], v104 offset0:132 offset1:134
	v_pk_mul_f32 v[22:23], v[22:23], v[2:3] op_sel_hi:[1,0]
	v_pk_mul_f32 v[24:25], v[24:25], v[2:3] op_sel_hi:[1,0]
	v_pk_mul_f32 v[26:27], v[26:27], v[2:3] op_sel_hi:[1,0]
	v_pk_mul_f32 v[28:29], v[28:29], v[2:3] op_sel_hi:[1,0]
	v_pk_mul_f32 v[30:31], v[30:31], v[2:3] op_sel_hi:[1,0]
	v_mov_b32_e32 v236, v0
	s_waitcnt lgkmcnt(1)
	v_mfma_f32_32x32x16_bf16 v[16:31], v[12:15], v[8:11], v[16:31]
	v_sub_f32 v8, v111, v0
	v_cvt_pk_bf16_f32 v9, v99, v100
	v_exp_f32_e32 v107, v8
	v_cvt_pk_bf16_f32 v8, v97, v98
	v_cvt_pk_bf16_f32 v10, v101, v102
	ds_read2_b64 v[12:15], v3 offset0:164 offset1:166
	v_cvt_pk_bf16_f32 v11, v103, v107
	s_waitcnt lgkmcnt(1)
	s_nop 0
	v_mfma_f32_32x32x16_bf16 v[64:79], v[4:7], v[8:11], v[64:79]
	v_add_f32 v4, v96, v97
	s_nop 0
	v_add_f32 v4, v4, v98
	s_nop 0
	v_add_f32 v4, v4, v99
	s_nop 0
	v_add_f32 v96, v4, v100
	v_sub_f32 v4, v80, v0
	s_waitcnt lgkmcnt(0)
	v_mfma_f32_32x32x16_bf16 v[48:63], v[12:15], v[8:11], v[48:63]
	v_exp_f32_e32 v80, v4
	ds_read2_b64 v[4:7], v105 offset0:196 offset1:198
	v_sub_f32 v12, v81, v0
	s_nop 0
	v_exp_f32_e32 v81, v12
	v_sub_f32 v12, v82, v0
	s_nop 0
	v_exp_f32_e32 v82, v12
	v_sub_f32 v12, v83, v0
	s_waitcnt lgkmcnt(0)
	v_mfma_f32_32x32x16_bf16 v[32:47], v[4:7], v[8:11], v[32:47]
	v_exp_f32_e32 v83, v12
	ds_read2_b64 v[12:15], v106 offset0:228 offset1:230
	v_sub_f32 v4, v84, v0
	s_nop 0
	v_exp_f32_e32 v84, v4
	v_sub_f32 v4, v85, v0
	s_nop 0
	v_exp_f32_e32 v85, v4
	v_sub_f32 v4, v86, v0
	s_waitcnt lgkmcnt(0)
	v_mfma_f32_32x32x16_bf16 v[16:31], v[12:15], v[8:11], v[16:31]
	v_exp_f32_e32 v86, v4
	ds_read2_b64 v[4:7], v104 offset0:136 offset1:138
	v_sub_f32 v8, v87, v0
	ds_read2_b64 v[12:15], v3 offset0:168 offset1:170
	v_exp_f32_e32 v87, v8
	v_cvt_pk_bf16_f32 v8, v80, v81
	v_cvt_pk_bf16_f32 v9, v82, v83
	v_cvt_pk_bf16_f32 v10, v84, v85
	v_cvt_pk_bf16_f32 v11, v86, v87
	s_waitcnt lgkmcnt(1)
	s_nop 0
	v_mfma_f32_32x32x16_bf16 v[64:79], v[4:7], v[8:11], v[64:79]
	v_add_f32 v4, v96, v101
	s_nop 0
	v_add_f32 v4, v4, v102
	s_nop 0
	v_add_f32 v4, v4, v103
	s_nop 0
	v_add_f32 v96, v4, v107
	v_sub_f32 v4, v88, v0
	s_waitcnt lgkmcnt(0)
	v_mfma_f32_32x32x16_bf16 v[48:63], v[12:15], v[8:11], v[48:63]
	v_exp_f32_e32 v88, v4
	ds_read2_b64 v[4:7], v105 offset0:200 offset1:202
	v_sub_f32 v12, v89, v0
	s_nop 0
	v_exp_f32_e32 v89, v12
	v_sub_f32 v12, v90, v0
	s_nop 0
	v_exp_f32_e32 v90, v12
	v_sub_f32 v12, v91, v0
	s_waitcnt lgkmcnt(0)
	v_mfma_f32_32x32x16_bf16 v[32:47], v[4:7], v[8:11], v[32:47]
	v_exp_f32_e32 v91, v12
	ds_read2_b64 v[12:15], v106 offset0:232 offset1:234
	v_sub_f32 v4, v92, v0
	s_nop 0
	v_exp_f32_e32 v92, v4
	v_sub_f32 v4, v93, v0
	s_nop 0
	v_exp_f32_e32 v93, v4
	v_sub_f32 v4, v94, v0
	s_waitcnt lgkmcnt(0)
	v_mfma_f32_32x32x16_bf16 v[16:31], v[12:15], v[8:11], v[16:31]
	v_exp_f32_e32 v94, v4
	ds_read2_b64 v[4:7], v104 offset0:140 offset1:142
	ds_read2_b64 v[12:15], v3 offset0:172 offset1:174
	v_sub_f32 v8, v95, v0
	v_cvt_pk_bf16_f32 v9, v90, v91
	v_exp_f32_e32 v95, v8
	v_cvt_pk_bf16_f32 v8, v88, v89
	v_cvt_pk_bf16_f32 v10, v92, v93
	v_add_f32 v3, v96, v80
	v_cvt_pk_bf16_f32 v11, v94, v95
	v_add_f32 v3, v3, v81
	s_nop 0
	v_add_f32 v3, v3, v82
	s_waitcnt lgkmcnt(1)
	v_mfma_f32_32x32x16_bf16 v[64:79], v[4:7], v[8:11], v[64:79]
	ds_read2_b64 v[4:7], v105 offset0:204 offset1:206
	v_add_f32 v3, v3, v83
	s_nop 0
	v_add_f32 v3, v3, v84
	s_nop 0
	v_add_f32 v3, v3, v85
	s_waitcnt lgkmcnt(1)
	v_mfma_f32_32x32x16_bf16 v[48:63], v[12:15], v[8:11], v[48:63]
	ds_read2_b64 v[12:15], v106 offset0:236 offset1:238
	v_add_f32 v3, v3, v86
	s_nop 0
	v_add_f32 v3, v3, v87
	s_nop 0
	v_add_f32 v3, v3, v88
	s_nop 0
	v_add_f32 v3, v3, v89
	s_waitcnt lgkmcnt(1)
	v_mfma_f32_32x32x16_bf16 v[32:47], v[4:7], v[8:11], v[32:47]
	v_add_f32 v3, v3, v90
	s_nop 0
	v_add_f32 v3, v3, v91
	s_nop 0
	v_add_f32 v3, v3, v92
	s_nop 0
	v_add_f32 v3, v3, v93
	s_waitcnt lgkmcnt(0)
	v_mfma_f32_32x32x16_bf16 v[16:31], v[12:15], v[8:11], v[16:31]
	v_add_f32 v3, v3, v94
	s_nop 0
	v_add_f32 v3, v3, v95
	s_nop 0
	v_fmac_f32_e32 v3, v246, v2
	v_mov_b32_e32 v246, v3
	s_branch .LBB0_310

.Lkdma_skip:
.LBB0_566:
	s_and_saveexec_b64 s[22:23], vcc
	s_cbranch_execz .LBB0_555
	ds_read_b128 v[196:199], v188
	ds_read_b128 v[202:205], v188 offset:32
	ds_read_b128 v[206:209], v188 offset:64
	ds_read_b128 v[210:213], v188 offset:96
	ds_read_b128 v[220:223], v188 offset:128
	ds_read_b128 v[224:227], v188 offset:160
	ds_read_b128 v[2:5], v188 offset:192
	ds_read_b128 v[6:9], v188 offset:224
	s_waitcnt lgkmcnt(7)
	v_mfma_f32_32x32x16_bf16 v[96:111], v[196:199], v[148:151], 0
	ds_read_b128 v[196:199], v188 offset:256
	s_waitcnt lgkmcnt(7)
	v_mfma_f32_32x32x16_bf16 v[96:111], v[202:205], v[144:147], v[96:111]
	ds_read_b128 v[202:205], v188 offset:288
	s_waitcnt lgkmcnt(7)
	v_mfma_f32_32x32x16_bf16 v[96:111], v[206:209], v[140:143], v[96:111]
	ds_read_b128 v[206:209], v188 offset:10752
	s_waitcnt lgkmcnt(7)
	v_mfma_f32_32x32x16_bf16 v[96:111], v[210:213], v[136:139], v[96:111]
	ds_read_b128 v[210:213], v188 offset:10784
	s_waitcnt lgkmcnt(7)
	v_mfma_f32_32x32x16_bf16 v[96:111], v[220:223], v[132:135], v[96:111]
	ds_read_b128 v[220:223], v188 offset:10816
	s_waitcnt lgkmcnt(7)
	v_mfma_f32_32x32x16_bf16 v[96:111], v[224:227], v[128:131], v[96:111]
	ds_read_b128 v[224:227], v188 offset:10848
	s_waitcnt lgkmcnt(7)
	v_mfma_f32_32x32x16_bf16 v[96:111], v[2:5], v[124:127], v[96:111]
	ds_read_b128 v[2:5], v188 offset:10880
	s_waitcnt lgkmcnt(7)
	v_mfma_f32_32x32x16_bf16 v[96:111], v[6:9], v[120:123], v[96:111]
	ds_read_b128 v[6:9], v188 offset:10912
	s_waitcnt lgkmcnt(7)
	v_mfma_f32_32x32x16_bf16 v[96:111], v[196:199], v[116:119], v[96:111]
	ds_read_b128 v[196:199], v188 offset:10944
	s_waitcnt lgkmcnt(7)
	v_mfma_f32_32x32x16_bf16 v[96:111], v[202:205], v[112:115], v[96:111]
	ds_read_b128 v[202:205], v188 offset:10976
	s_waitcnt lgkmcnt(7)
	v_mfma_f32_32x32x16_bf16 v[80:95], v[206:209], v[148:151], 0
	ds_read_b128 v[206:209], v188 offset:11008
	s_waitcnt lgkmcnt(7)
	v_mfma_f32_32x32x16_bf16 v[80:95], v[210:213], v[144:147], v[80:95]
	ds_read_b128 v[210:213], v188 offset:11040
	s_waitcnt lgkmcnt(7)
	v_mfma_f32_32x32x16_bf16 v[80:95], v[220:223], v[140:143], v[80:95]
	s_waitcnt lgkmcnt(6)
	v_mfma_f32_32x32x16_bf16 v[80:95], v[224:227], v[136:139], v[80:95]
	s_waitcnt lgkmcnt(5)
	v_mfma_f32_32x32x16_bf16 v[80:95], v[2:5], v[132:135], v[80:95]
	s_waitcnt lgkmcnt(4)
	v_mfma_f32_32x32x16_bf16 v[80:95], v[6:9], v[128:131], v[80:95]
	s_waitcnt lgkmcnt(3)
	v_mfma_f32_32x32x16_bf16 v[80:95], v[196:199], v[124:127], v[80:95]
	v_max_f32_e32 v0, v97, v97
	v_max_f32_e32 v10, v96, v96
	v_max_f32_e32 v0, v10, v0
	v_max3_f32 v0, v0, v98, v99
	v_max3_f32 v0, v0, v100, v101
	v_max3_f32 v0, v0, v102, v103
	v_max3_f32 v0, v0, v104, v105
	v_max3_f32 v0, v0, v106, v107
	v_max3_f32 v0, v0, v108, v109
	v_max3_f32 v0, v0, v110, v111
	v_and_b32_e32 v3, 64, v218
	v_xor_b32_e32 v2, 32, v218
	v_add_u32_e32 v3, 64, v3
	v_cmp_lt_i32_e64 s[12:13], v2, v3
	s_nop 1
	v_cndmask_b32_e64 v2, v218, v2, s[12:13]
	s_waitcnt lgkmcnt(2)
	v_mfma_f32_32x32x16_bf16 v[80:95], v[202:205], v[120:123], v[80:95]
	s_waitcnt lgkmcnt(1)
	v_mfma_f32_32x32x16_bf16 v[80:95], v[206:209], v[116:119], v[80:95]
	s_waitcnt lgkmcnt(0)
	v_mfma_f32_32x32x16_bf16 v[80:95], v[210:213], v[112:115], v[80:95]
	v_lshlrev_b32_e32 v2, 2, v2
	s_nop 10
	v_max3_f32 v0, v0, v80, v81
	v_max3_f32 v0, v0, v82, v83
	v_max3_f32 v0, v0, v84, v85
	v_max3_f32 v0, v0, v86, v87
	v_max3_f32 v0, v0, v88, v89
	v_max3_f32 v0, v0, v90, v91
	v_max3_f32 v0, v0, v92, v93
	v_max3_f32 v0, v0, v94, v95
	v_mov_b32_e32 v2, v0
	s_nop 1
	v_permlane32_swap_b32_e32 v2, v0
	s_nop 1
	s_cmp_ge_u32 s58, s27
	s_cbranch_scc1 .Lvmid_skip
	s_waitcnt vmcnt(2)
	v_xor_b32_e32 v157, 0x10000, v192
	v_xor_b32_e32 v162, 0x10000, v193
	ds_write2_b64 v157, v[168:169], v[170:171] offset1:1
	ds_write2_b64 v162, v[164:165], v[166:167] offset1:1

.LBB0_598:
	s_and_saveexec_b64 s[24:25], s[6:7]
	s_cbranch_execz .LBB0_587
	ds_read_b128 v[194:197], v185
	ds_read_b128 v[202:205], v185 offset:32
	ds_read_b128 v[206:209], v185 offset:64
	ds_read_b128 v[210:213], v185 offset:96
	ds_read_b128 v[220:223], v185 offset:128
	ds_read_b128 v[224:227], v185 offset:160
	ds_read_b128 v[2:5], v185 offset:192
	ds_read_b128 v[6:9], v185 offset:224
	s_waitcnt lgkmcnt(7)
	v_mfma_f32_32x32x16_bf16 v[96:111], v[194:197], v[148:151], 0
	ds_read_b128 v[194:197], v185 offset:256
	s_waitcnt lgkmcnt(7)
	v_mfma_f32_32x32x16_bf16 v[96:111], v[202:205], v[144:147], v[96:111]
	ds_read_b128 v[202:205], v185 offset:288
	s_waitcnt lgkmcnt(7)
	v_mfma_f32_32x32x16_bf16 v[96:111], v[206:209], v[140:143], v[96:111]
	ds_read_b128 v[206:209], v185 offset:10752
	s_waitcnt lgkmcnt(7)
	v_mfma_f32_32x32x16_bf16 v[96:111], v[210:213], v[136:139], v[96:111]
	ds_read_b128 v[210:213], v185 offset:10784
	s_waitcnt lgkmcnt(7)
	v_mfma_f32_32x32x16_bf16 v[96:111], v[220:223], v[132:135], v[96:111]
	ds_read_b128 v[220:223], v185 offset:10816
	s_waitcnt lgkmcnt(7)
	v_mfma_f32_32x32x16_bf16 v[96:111], v[224:227], v[128:131], v[96:111]
	ds_read_b128 v[224:227], v185 offset:10848
	s_waitcnt lgkmcnt(7)
	v_mfma_f32_32x32x16_bf16 v[96:111], v[2:5], v[124:127], v[96:111]
	ds_read_b128 v[2:5], v185 offset:10880
	s_waitcnt lgkmcnt(7)
	v_mfma_f32_32x32x16_bf16 v[96:111], v[6:9], v[120:123], v[96:111]
	ds_read_b128 v[6:9], v185 offset:10912
	s_waitcnt lgkmcnt(7)
	v_mfma_f32_32x32x16_bf16 v[96:111], v[194:197], v[116:119], v[96:111]
	ds_read_b128 v[194:197], v185 offset:10944
	s_waitcnt lgkmcnt(7)
	v_mfma_f32_32x32x16_bf16 v[96:111], v[202:205], v[112:115], v[96:111]
	ds_read_b128 v[202:205], v185 offset:10976
	s_waitcnt lgkmcnt(7)
	v_mfma_f32_32x32x16_bf16 v[80:95], v[206:209], v[148:151], 0
	ds_read_b128 v[206:209], v185 offset:11008
	s_waitcnt lgkmcnt(7)
	v_mfma_f32_32x32x16_bf16 v[80:95], v[210:213], v[144:147], v[80:95]
	ds_read_b128 v[210:213], v185 offset:11040
	s_waitcnt lgkmcnt(7)
	v_mfma_f32_32x32x16_bf16 v[80:95], v[220:223], v[140:143], v[80:95]
	s_waitcnt lgkmcnt(6)
	v_mfma_f32_32x32x16_bf16 v[80:95], v[224:227], v[136:139], v[80:95]
	s_waitcnt lgkmcnt(5)
	v_mfma_f32_32x32x16_bf16 v[80:95], v[2:5], v[132:135], v[80:95]
	s_waitcnt lgkmcnt(4)
	v_mfma_f32_32x32x16_bf16 v[80:95], v[6:9], v[128:131], v[80:95]
	s_waitcnt lgkmcnt(3)
	v_mfma_f32_32x32x16_bf16 v[80:95], v[194:197], v[124:127], v[80:95]
	v_max_f32_e32 v0, v97, v97
	v_max_f32_e32 v10, v96, v96
	v_max_f32_e32 v0, v10, v0
	v_max3_f32 v0, v0, v98, v99
	v_max3_f32 v0, v0, v100, v101
	v_max3_f32 v0, v0, v102, v103
	v_max3_f32 v0, v0, v104, v105
	v_max3_f32 v0, v0, v106, v107
	v_max3_f32 v0, v0, v108, v109
	v_max3_f32 v0, v0, v110, v111
	v_and_b32_e32 v3, 64, v218
	v_xor_b32_e32 v2, 32, v218
	v_add_u32_e32 v3, 64, v3
	v_cmp_lt_i32_e32 vcc, v2, v3
	s_nop 1
	v_cndmask_b32_e32 v2, v218, v2, vcc
	s_waitcnt lgkmcnt(2)
	v_mfma_f32_32x32x16_bf16 v[80:95], v[202:205], v[120:123], v[80:95]
	s_waitcnt lgkmcnt(1)
	v_mfma_f32_32x32x16_bf16 v[80:95], v[206:209], v[116:119], v[80:95]
	s_waitcnt lgkmcnt(0)
	v_mfma_f32_32x32x16_bf16 v[80:95], v[210:213], v[112:115], v[80:95]
	v_lshlrev_b32_e32 v2, 2, v2
	s_nop 10
	v_max3_f32 v0, v0, v80, v81
	v_max3_f32 v0, v0, v82, v83
	v_max3_f32 v0, v0, v84, v85
	v_max3_f32 v0, v0, v86, v87
	v_max3_f32 v0, v0, v88, v89
	v_max3_f32 v0, v0, v90, v91
	v_max3_f32 v0, v0, v92, v93
	v_max3_f32 v0, v0, v94, v95
	v_mov_b32_e32 v2, v0
	s_nop 1
	v_permlane32_swap_b32_e32 v2, v0
	s_nop 1
	v_add_u32_e32 v224, 0x5000, v191
	v_add_u32_e32 v225, 0x6000, v191
	v_add_u32_e32 v226, 0x7000, v191
	v_add_u32_e32 v227, 0x8000, v191
	ds_read2_b64 v[194:197], v224 offset0:128 offset1:130
	ds_read2_b64 v[202:205], v225 offset0:160 offset1:162
	ds_read2_b64 v[206:209], v226 offset0:192 offset1:194
	ds_read2_b64 v[210:213], v227 offset0:224 offset1:226
	ds_read2_b64 v[220:223], v224 offset0:132 offset1:134
	v_max3_f32 v0, v192, v0, v2
	v_sub_f32 v4, v97, v0
	v_sub_f32 v3, v96, v0
	v_sub_f32 v5, v100, v0
	v_sub_f32_e32 v2, v192, v0
	v_exp_f32_e32 v8, v4
	v_sub_f32 v4, v98, v0
	v_exp_f32_e32 v3, v3
	v_exp_f32_e32 v9, v4
	v_sub_f32 v4, v99, v0
	v_exp_f32_e32 v11, v5
	v_exp_f32_e32 v10, v4
	v_add_f32 v4, v1, v3
	v_sub_f32 v5, v101, v0
	v_exp_f32_e32 v2, v2
	v_add_f32 v4, v4, v8
	v_exp_f32_e32 v12, v5
	v_add_f32 v4, v4, v9
	v_sub_f32 v5, v102, v0
	v_cvt_pk_bf16_f32 v8, v3, v8
	v_add_f32 v4, v4, v10
	v_exp_f32_e32 v13, v5
	v_add_f32 v4, v4, v11
	v_sub_f32 v5, v103, v0
	v_add_f32 v4, v4, v12
	v_exp_f32_e32 v14, v5
	v_add_f32 v4, v4, v13
	v_cvt_pk_bf16_f32 v9, v9, v10
	v_add_f32 v96, v4, v14
	v_sub_f32 v4, v104, v0
	v_exp_f32_e32 v97, v4
	v_sub_f32 v4, v105, v0
	v_cvt_pk_bf16_f32 v10, v11, v12
	v_exp_f32_e32 v98, v4
	v_sub_f32 v4, v106, v0
	v_cvt_pk_bf16_f32 v11, v13, v14
	v_exp_f32_e32 v99, v4
	v_sub_f32 v4, v107, v0
	v_exp_f32_e32 v100, v4
	v_sub_f32 v4, v108, v0
	v_pk_mul_f32 v[64:65], v[64:65], v[2:3] op_sel_hi:[1,0]
	v_pk_mul_f32 v[66:67], v[66:67], v[2:3] op_sel_hi:[1,0]
	v_pk_mul_f32 v[68:69], v[68:69], v[2:3] op_sel_hi:[1,0]
	s_nop 0
	v_exp_f32_e32 v101, v4
	v_sub_f32 v4, v109, v0
	v_pk_mul_f32 v[70:71], v[70:71], v[2:3] op_sel_hi:[1,0]
	v_pk_mul_f32 v[72:73], v[72:73], v[2:3] op_sel_hi:[1,0]
	s_nop 0
	v_exp_f32_e32 v102, v4
	v_sub_f32 v4, v110, v0
	v_pk_mul_f32 v[74:75], v[74:75], v[2:3] op_sel_hi:[1,0]
	v_pk_mul_f32 v[76:77], v[76:77], v[2:3] op_sel_hi:[1,0]
	v_pk_mul_f32 v[78:79], v[78:79], v[2:3] op_sel_hi:[1,0]
	s_nop 0
	v_exp_f32_e32 v103, v4
	s_waitcnt lgkmcnt(4)
	v_mfma_f32_32x32x16_bf16 v[64:79], v[194:197], v[8:11], v[64:79]
	ds_read2_b64 v[194:197], v225 offset0:164 offset1:166
	v_pk_mul_f32 v[48:49], v[48:49], v[2:3] op_sel_hi:[1,0]
	v_pk_mul_f32 v[50:51], v[50:51], v[2:3] op_sel_hi:[1,0]
	v_pk_mul_f32 v[52:53], v[52:53], v[2:3] op_sel_hi:[1,0]
	v_pk_mul_f32 v[54:55], v[54:55], v[2:3] op_sel_hi:[1,0]
	v_pk_mul_f32 v[56:57], v[56:57], v[2:3] op_sel_hi:[1,0]
	v_pk_mul_f32 v[58:59], v[58:59], v[2:3] op_sel_hi:[1,0]
	v_pk_mul_f32 v[60:61], v[60:61], v[2:3] op_sel_hi:[1,0]
	v_pk_mul_f32 v[62:63], v[62:63], v[2:3] op_sel_hi:[1,0]
	s_waitcnt lgkmcnt(4)
	v_mfma_f32_32x32x16_bf16 v[48:63], v[202:205], v[8:11], v[48:63]
	ds_read2_b64 v[202:205], v226 offset0:196 offset1:198
	v_pk_mul_f32 v[32:33], v[32:33], v[2:3] op_sel_hi:[1,0]
	v_pk_mul_f32 v[34:35], v[34:35], v[2:3] op_sel_hi:[1,0]
	v_pk_mul_f32 v[36:37], v[36:37], v[2:3] op_sel_hi:[1,0]
	v_pk_mul_f32 v[38:39], v[38:39], v[2:3] op_sel_hi:[1,0]
	v_pk_mul_f32 v[40:41], v[40:41], v[2:3] op_sel_hi:[1,0]
	v_pk_mul_f32 v[42:43], v[42:43], v[2:3] op_sel_hi:[1,0]
	v_pk_mul_f32 v[44:45], v[44:45], v[2:3] op_sel_hi:[1,0]
	v_pk_mul_f32 v[46:47], v[46:47], v[2:3] op_sel_hi:[1,0]
	v_pk_mul_f32 v[16:17], v[16:17], v[2:3] op_sel_hi:[1,0]
	v_pk_mul_f32 v[18:19], v[18:19], v[2:3] op_sel_hi:[1,0]
	v_pk_mul_f32 v[20:21], v[20:21], v[2:3] op_sel_hi:[1,0]
	s_waitcnt lgkmcnt(4)
	v_mfma_f32_32x32x16_bf16 v[32:47], v[206:209], v[8:11], v[32:47]
	ds_read2_b64 v[206:209], v227 offset0:228 offset1:230
	v_pk_mul_f32 v[22:23], v[22:23], v[2:3] op_sel_hi:[1,0]
	v_pk_mul_f32 v[24:25], v[24:25], v[2:3] op_sel_hi:[1,0]
	v_pk_mul_f32 v[26:27], v[26:27], v[2:3] op_sel_hi:[1,0]
	v_pk_mul_f32 v[28:29], v[28:29], v[2:3] op_sel_hi:[1,0]
	v_pk_mul_f32 v[30:31], v[30:31], v[2:3] op_sel_hi:[1,0]
	v_mov_b32_e32 v192, v0
	s_waitcnt lgkmcnt(4)
	v_mfma_f32_32x32x16_bf16 v[16:31], v[210:213], v[8:11], v[16:31]
	ds_read2_b64 v[210:213], v224 offset0:136 offset1:138
	v_sub_f32 v8, v111, v0
	v_cvt_pk_bf16_f32 v9, v99, v100
	v_exp_f32_e32 v107, v8
	v_cvt_pk_bf16_f32 v8, v97, v98
	v_cvt_pk_bf16_f32 v10, v101, v102
	v_cvt_pk_bf16_f32 v11, v103, v107
	s_nop 0
	s_waitcnt lgkmcnt(4)
	v_mfma_f32_32x32x16_bf16 v[64:79], v[220:223], v[8:11], v[64:79]
	ds_read2_b64 v[220:223], v225 offset0:168 offset1:170
	v_add_f32 v4, v96, v97
	s_nop 0
	v_add_f32 v4, v4, v98
	s_nop 0
	v_add_f32 v4, v4, v99
	s_nop 0
	v_add_f32 v96, v4, v100
	v_sub_f32 v4, v80, v0
	s_waitcnt lgkmcnt(4)
	v_mfma_f32_32x32x16_bf16 v[48:63], v[194:197], v[8:11], v[48:63]
	ds_read2_b64 v[194:197], v226 offset0:200 offset1:202
	v_exp_f32_e32 v80, v4
	v_sub_f32 v12, v81, v0
	s_nop 0
	v_exp_f32_e32 v81, v12
	v_sub_f32 v12, v82, v0
	s_nop 0
	v_exp_f32_e32 v82, v12
	v_sub_f32 v12, v83, v0
	s_waitcnt lgkmcnt(4)
	v_mfma_f32_32x32x16_bf16 v[32:47], v[202:205], v[8:11], v[32:47]
	ds_read2_b64 v[202:205], v227 offset0:232 offset1:234
	v_exp_f32_e32 v83, v12
	v_sub_f32 v4, v84, v0
	s_nop 0
	v_exp_f32_e32 v84, v4
	v_sub_f32 v4, v85, v0
	s_nop 0
	v_exp_f32_e32 v85, v4
	v_sub_f32 v4, v86, v0
	s_waitcnt lgkmcnt(4)
	v_mfma_f32_32x32x16_bf16 v[16:31], v[206:209], v[8:11], v[16:31]
	ds_read2_b64 v[206:209], v224 offset0:140 offset1:142
	v_exp_f32_e32 v86, v4
	v_sub_f32 v8, v87, v0
	v_exp_f32_e32 v87, v8
	v_cvt_pk_bf16_f32 v8, v80, v81
	v_cvt_pk_bf16_f32 v9, v82, v83
	v_cvt_pk_bf16_f32 v10, v84, v85
	v_cvt_pk_bf16_f32 v11, v86, v87
	s_nop 0
	s_waitcnt lgkmcnt(4)
	v_mfma_f32_32x32x16_bf16 v[64:79], v[210:213], v[8:11], v[64:79]
	ds_read2_b64 v[210:213], v225 offset0:172 offset1:174
	v_add_f32 v4, v96, v101
	s_nop 0
	v_add_f32 v4, v4, v102
	s_nop 0
	v_add_f32 v4, v4, v103
	s_nop 0
	v_add_f32 v96, v4, v107
	v_sub_f32 v4, v88, v0
	s_waitcnt lgkmcnt(4)
	v_mfma_f32_32x32x16_bf16 v[48:63], v[220:223], v[8:11], v[48:63]
	ds_read2_b64 v[220:223], v226 offset0:204 offset1:206
	v_exp_f32_e32 v88, v4
	v_sub_f32 v12, v89, v0
	s_nop 0
	v_exp_f32_e32 v89, v12
	v_sub_f32 v12, v90, v0
	s_nop 0
	v_exp_f32_e32 v90, v12
	v_sub_f32 v12, v91, v0
	s_waitcnt lgkmcnt(4)
	v_mfma_f32_32x32x16_bf16 v[32:47], v[194:197], v[8:11], v[32:47]
	ds_read2_b64 v[194:197], v227 offset0:236 offset1:238
	v_exp_f32_e32 v91, v12
	v_sub_f32 v4, v92, v0
	s_nop 0
	v_exp_f32_e32 v92, v4
	v_sub_f32 v4, v93, v0
	s_nop 0
	v_exp_f32_e32 v93, v4
	v_sub_f32 v4, v94, v0
	s_waitcnt lgkmcnt(4)
	v_mfma_f32_32x32x16_bf16 v[16:31], v[202:205], v[8:11], v[16:31]
	v_exp_f32_e32 v94, v4
	v_sub_f32 v8, v95, v0
	v_cvt_pk_bf16_f32 v9, v90, v91
	v_exp_f32_e32 v95, v8
	v_cvt_pk_bf16_f32 v8, v88, v89
	v_cvt_pk_bf16_f32 v10, v92, v93
	v_add_f32 v3, v96, v80
	v_cvt_pk_bf16_f32 v11, v94, v95
	v_add_f32 v3, v3, v81
	s_nop 0
	v_add_f32 v3, v3, v82
	s_waitcnt lgkmcnt(3)
	v_mfma_f32_32x32x16_bf16 v[64:79], v[206:209], v[8:11], v[64:79]
	v_add_f32 v3, v3, v83
	s_nop 0
	v_add_f32 v3, v3, v84
	s_nop 0
	v_add_f32 v3, v3, v85
	s_waitcnt lgkmcnt(2)
	v_mfma_f32_32x32x16_bf16 v[48:63], v[210:213], v[8:11], v[48:63]
	v_add_f32 v3, v3, v86
	s_nop 0
	v_add_f32 v3, v3, v87
	s_nop 0
	v_add_f32 v3, v3, v88
	s_nop 0
	v_add_f32 v3, v3, v89
	s_waitcnt lgkmcnt(1)
	v_mfma_f32_32x32x16_bf16 v[32:47], v[220:223], v[8:11], v[32:47]
	v_add_f32 v3, v3, v90
	s_nop 0
	v_add_f32 v3, v3, v91
	s_nop 0
	v_add_f32 v3, v3, v92
	s_nop 0
	v_add_f32 v3, v3, v93
	s_waitcnt lgkmcnt(0)
	v_mfma_f32_32x32x16_bf16 v[16:31], v[194:197], v[8:11], v[16:31]
	v_add_f32 v3, v3, v94
	s_nop 0
	v_add_f32 v3, v3, v95
	s_nop 0
	v_fmac_f32_e32 v3, v184, v2
	v_mov_b32_e32 v184, v3
	s_branch .LBB0_587

.LBB0_1215:
	s_and_saveexec_b64 s[70:71], s[8:9]
	s_cbranch_execz .LBB0_1202
	ds_read_b128 v[220:223], v245
	ds_read_b128 v[224:227], v245 offset:32
	ds_read_b128 v[2:5], v245 offset:64
	ds_read_b128 v[6:9], v245 offset:96
	s_waitcnt lgkmcnt(3)
	v_mfma_f32_32x32x16_bf16 v[96:111], v[220:223], v[172:175], 0
	ds_read_b128 v[220:223], v245 offset:128
	s_waitcnt lgkmcnt(3)
	v_mfma_f32_32x32x16_bf16 v[96:111], v[224:227], v[168:171], v[96:111]
	ds_read_b128 v[224:227], v245 offset:160
	s_waitcnt lgkmcnt(3)
	v_mfma_f32_32x32x16_bf16 v[96:111], v[2:5], v[164:167], v[96:111]
	ds_read_b128 v[2:5], v245 offset:192
	s_waitcnt lgkmcnt(3)
	v_mfma_f32_32x32x16_bf16 v[96:111], v[6:9], v[160:163], v[96:111]
	ds_read_b128 v[6:9], v245 offset:224
	s_waitcnt lgkmcnt(3)
	v_mfma_f32_32x32x16_bf16 v[96:111], v[220:223], v[156:159], v[96:111]
	ds_read_b128 v[220:223], v245 offset:256
	s_waitcnt lgkmcnt(3)
	v_mfma_f32_32x32x16_bf16 v[96:111], v[224:227], v[152:155], v[96:111]
	ds_read_b128 v[224:227], v245 offset:288
	s_waitcnt lgkmcnt(3)
	v_mfma_f32_32x32x16_bf16 v[96:111], v[2:5], v[148:151], v[96:111]
	ds_read_b128 v[2:5], v245 offset:320
	s_waitcnt lgkmcnt(3)
	v_mfma_f32_32x32x16_bf16 v[96:111], v[6:9], v[144:147], v[96:111]
	ds_read_b128 v[6:9], v245 offset:352
	s_waitcnt lgkmcnt(3)
	v_mfma_f32_32x32x16_bf16 v[96:111], v[220:223], v[140:143], v[96:111]
	ds_read_b128 v[220:223], v245 offset:384
	s_waitcnt lgkmcnt(3)
	v_mfma_f32_32x32x16_bf16 v[96:111], v[224:227], v[136:139], v[96:111]
	ds_read_b128 v[224:227], v245 offset:416
	s_waitcnt lgkmcnt(3)
	v_mfma_f32_32x32x16_bf16 v[96:111], v[2:5], v[132:135], v[96:111]
	ds_read_b128 v[2:5], v245 offset:448
	s_waitcnt lgkmcnt(3)
	v_mfma_f32_32x32x16_bf16 v[96:111], v[6:9], v[128:131], v[96:111]
	ds_read_b128 v[6:9], v245 offset:480
	s_waitcnt lgkmcnt(3)
	v_mfma_f32_32x32x16_bf16 v[96:111], v[220:223], v[124:127], v[96:111]
	ds_read_b128 v[220:223], v245 offset:16896
	s_waitcnt lgkmcnt(3)
	v_mfma_f32_32x32x16_bf16 v[96:111], v[224:227], v[120:123], v[96:111]
	ds_read_b128 v[224:227], v245 offset:16928
	s_waitcnt lgkmcnt(3)
	v_mfma_f32_32x32x16_bf16 v[96:111], v[2:5], v[116:119], v[96:111]
	ds_read_b128 v[2:5], v245 offset:16960
	s_waitcnt lgkmcnt(3)
	v_mfma_f32_32x32x16_bf16 v[96:111], v[6:9], v[112:115], v[96:111]
	ds_read_b128 v[6:9], v245 offset:16992
	s_waitcnt lgkmcnt(3)
	v_mfma_f32_32x32x16_bf16 v[80:95], v[220:223], v[172:175], 0
	ds_read_b128 v[220:223], v245 offset:17024
	s_waitcnt lgkmcnt(3)
	v_mfma_f32_32x32x16_bf16 v[80:95], v[224:227], v[168:171], v[80:95]
	ds_read_b128 v[224:227], v245 offset:17056
	s_waitcnt lgkmcnt(3)
	v_mfma_f32_32x32x16_bf16 v[80:95], v[2:5], v[164:167], v[80:95]
	ds_read_b128 v[2:5], v245 offset:17088
	s_waitcnt lgkmcnt(3)
	v_mfma_f32_32x32x16_bf16 v[80:95], v[6:9], v[160:163], v[80:95]
	ds_read_b128 v[6:9], v245 offset:17120
	s_waitcnt lgkmcnt(3)
	v_mfma_f32_32x32x16_bf16 v[80:95], v[220:223], v[156:159], v[80:95]
	ds_read_b128 v[220:223], v245 offset:17152
	s_waitcnt lgkmcnt(3)
	v_mfma_f32_32x32x16_bf16 v[80:95], v[224:227], v[152:155], v[80:95]
	ds_read_b128 v[224:227], v245 offset:17184
	s_waitcnt lgkmcnt(3)
	v_mfma_f32_32x32x16_bf16 v[80:95], v[2:5], v[148:151], v[80:95]
	ds_read_b128 v[2:5], v245 offset:17216
	s_waitcnt lgkmcnt(3)
	v_mfma_f32_32x32x16_bf16 v[80:95], v[6:9], v[144:147], v[80:95]
	ds_read_b128 v[6:9], v245 offset:17248
	s_waitcnt lgkmcnt(3)
	v_mfma_f32_32x32x16_bf16 v[80:95], v[220:223], v[140:143], v[80:95]
	ds_read_b128 v[220:223], v245 offset:17280
	s_waitcnt lgkmcnt(3)
	v_mfma_f32_32x32x16_bf16 v[80:95], v[224:227], v[136:139], v[80:95]
	ds_read_b128 v[224:227], v245 offset:17312
	s_waitcnt lgkmcnt(3)
	v_mfma_f32_32x32x16_bf16 v[80:95], v[2:5], v[132:135], v[80:95]
	ds_read_b128 v[2:5], v245 offset:17344
	s_waitcnt lgkmcnt(3)
	v_mfma_f32_32x32x16_bf16 v[80:95], v[6:9], v[128:131], v[80:95]
	ds_read_b128 v[6:9], v245 offset:17376
	s_waitcnt lgkmcnt(3)
	v_mfma_f32_32x32x16_bf16 v[80:95], v[220:223], v[124:127], v[80:95]
	s_waitcnt lgkmcnt(2)
	v_mfma_f32_32x32x16_bf16 v[80:95], v[224:227], v[120:123], v[80:95]
	s_waitcnt lgkmcnt(1)
	v_mfma_f32_32x32x16_bf16 v[80:95], v[2:5], v[116:119], v[80:95]
	s_waitcnt lgkmcnt(0)
	v_mfma_f32_32x32x16_bf16 v[80:95], v[6:9], v[112:115], v[80:95]
	v_max_f32_e32 v0, v97, v97
	v_max_f32_e32 v10, v96, v96
	v_max_f32_e32 v0, v10, v0
	v_max3_f32 v0, v0, v98, v99
	v_max3_f32 v0, v0, v100, v101
	v_max3_f32 v0, v0, v102, v103
	v_max3_f32 v0, v0, v104, v105
	v_max3_f32 v0, v0, v106, v107
	v_max3_f32 v0, v0, v108, v109
	v_max3_f32 v0, v0, v110, v111
	v_and_b32_e32 v3, 64, v218
	v_xor_b32_e32 v2, 32, v218
	v_add_u32_e32 v3, 64, v3
	v_cmp_lt_i32_e32 vcc, v2, v3
	s_nop 1
	v_cndmask_b32_e32 v2, v218, v2, vcc
	v_lshlrev_b32_e32 v2, 2, v2
	s_nop 10
	v_max3_f32 v0, v0, v80, v81
	v_max3_f32 v0, v0, v82, v83
	v_max3_f32 v0, v0, v84, v85
	v_max3_f32 v0, v0, v86, v87
	v_max3_f32 v0, v0, v88, v89
	v_max3_f32 v0, v0, v90, v91
	v_max3_f32 v0, v0, v92, v93
	v_max3_f32 v0, v0, v94, v95
	v_mov_b32_e32 v2, v0
	s_nop 1
	v_permlane32_swap_b32_e32 v2, v0
	s_nop 1
	v_max3_f32 v0, v236, v0, v2
	v_sub_f32 v4, v97, v0
	v_sub_f32 v3, v96, v0
	v_sub_f32 v5, v100, v0
	v_sub_f32_e32 v2, v236, v0
	v_exp_f32_e32 v8, v4
	v_sub_f32 v4, v98, v0
	v_exp_f32_e32 v3, v3
	v_exp_f32_e32 v9, v4
	v_sub_f32 v4, v99, v0
	v_exp_f32_e32 v11, v5
	v_exp_f32_e32 v10, v4
	v_add_f32 v4, v1, v3
	v_sub_f32 v5, v101, v0
	v_exp_f32_e32 v2, v2
	v_add_f32 v4, v4, v8
	v_exp_f32_e32 v12, v5
	v_add_f32 v4, v4, v9
	v_sub_f32 v5, v102, v0
	v_cvt_pk_bf16_f32 v8, v3, v8
	v_add_f32 v4, v4, v10
	v_exp_f32_e32 v13, v5
	v_add_f32 v4, v4, v11
	v_sub_f32 v5, v103, v0
	v_add_u32_e32 v3, 0x9000, v219
	v_add_f32 v4, v4, v12
	v_exp_f32_e32 v14, v5
	v_add_f32 v4, v4, v13
	v_cvt_pk_bf16_f32 v9, v9, v10
	v_add_f32 v96, v4, v14
	v_sub_f32 v4, v104, v0
	v_add_u32_e32 v104, 0x8000, v219
	v_exp_f32_e32 v97, v4
	v_sub_f32 v4, v105, v0
	v_cvt_pk_bf16_f32 v10, v11, v12
	v_exp_f32_e32 v98, v4
	v_sub_f32 v4, v106, v0
	v_cvt_pk_bf16_f32 v11, v13, v14
	v_exp_f32_e32 v99, v4
	v_sub_f32 v4, v107, v0
	ds_read2_b64 v[12:15], v3 offset0:160 offset1:162
	v_exp_f32_e32 v100, v4
	v_sub_f32 v4, v108, v0
	v_pk_mul_f32 v[64:65], v[64:65], v[2:3] op_sel_hi:[1,0]
	v_pk_mul_f32 v[66:67], v[66:67], v[2:3] op_sel_hi:[1,0]
	v_pk_mul_f32 v[68:69], v[68:69], v[2:3] op_sel_hi:[1,0]
	s_nop 0
	v_exp_f32_e32 v101, v4
	v_sub_f32 v4, v109, v0
	v_pk_mul_f32 v[70:71], v[70:71], v[2:3] op_sel_hi:[1,0]
	v_pk_mul_f32 v[72:73], v[72:73], v[2:3] op_sel_hi:[1,0]
	s_nop 0
	v_exp_f32_e32 v102, v4
	v_sub_f32 v4, v110, v0
	v_pk_mul_f32 v[74:75], v[74:75], v[2:3] op_sel_hi:[1,0]
	v_pk_mul_f32 v[76:77], v[76:77], v[2:3] op_sel_hi:[1,0]
	v_pk_mul_f32 v[78:79], v[78:79], v[2:3] op_sel_hi:[1,0]
	s_nop 0
	v_exp_f32_e32 v103, v4
	ds_read2_b64 v[4:7], v104 offset0:128 offset1:130
	v_add_u32_e32 v105, 0xa000, v219
	s_waitcnt lgkmcnt(0)
	v_mfma_f32_32x32x16_bf16 v[64:79], v[4:7], v[8:11], v[64:79]
	ds_read2_b64 v[4:7], v105 offset0:192 offset1:194
	v_pk_mul_f32 v[48:49], v[48:49], v[2:3] op_sel_hi:[1,0]
	v_pk_mul_f32 v[50:51], v[50:51], v[2:3] op_sel_hi:[1,0]
	v_pk_mul_f32 v[52:53], v[52:53], v[2:3] op_sel_hi:[1,0]
	v_pk_mul_f32 v[54:55], v[54:55], v[2:3] op_sel_hi:[1,0]
	v_pk_mul_f32 v[56:57], v[56:57], v[2:3] op_sel_hi:[1,0]
	v_pk_mul_f32 v[58:59], v[58:59], v[2:3] op_sel_hi:[1,0]
	v_pk_mul_f32 v[60:61], v[60:61], v[2:3] op_sel_hi:[1,0]
	v_pk_mul_f32 v[62:63], v[62:63], v[2:3] op_sel_hi:[1,0]
	v_add_u32_e32 v106, 0xb000, v219
	v_mfma_f32_32x32x16_bf16 v[48:63], v[12:15], v[8:11], v[48:63]
	ds_read2_b64 v[12:15], v106 offset0:224 offset1:226
	v_pk_mul_f32 v[32:33], v[32:33], v[2:3] op_sel_hi:[1,0]
	v_pk_mul_f32 v[34:35], v[34:35], v[2:3] op_sel_hi:[1,0]
	v_pk_mul_f32 v[36:37], v[36:37], v[2:3] op_sel_hi:[1,0]
	v_pk_mul_f32 v[38:39], v[38:39], v[2:3] op_sel_hi:[1,0]
	v_pk_mul_f32 v[40:41], v[40:41], v[2:3] op_sel_hi:[1,0]
	v_pk_mul_f32 v[42:43], v[42:43], v[2:3] op_sel_hi:[1,0]
	v_pk_mul_f32 v[44:45], v[44:45], v[2:3] op_sel_hi:[1,0]
	v_pk_mul_f32 v[46:47], v[46:47], v[2:3] op_sel_hi:[1,0]
	v_pk_mul_f32 v[16:17], v[16:17], v[2:3] op_sel_hi:[1,0]
	v_pk_mul_f32 v[18:19], v[18:19], v[2:3] op_sel_hi:[1,0]
	v_pk_mul_f32 v[20:21], v[20:21], v[2:3] op_sel_hi:[1,0]
	s_waitcnt lgkmcnt(1)
	v_mfma_f32_32x32x16_bf16 v[32:47], v[4:7], v[8:11], v[32:47]
	ds_read2_b64 v[4:7], v104 offset0:132 offset1:134
	v_pk_mul_f32 v[22:23], v[22:23], v[2:3] op_sel_hi:[1,0]
	v_pk_mul_f32 v[24:25], v[24:25], v[2:3] op_sel_hi:[1,0]
	v_pk_mul_f32 v[26:27], v[26:27], v[2:3] op_sel_hi:[1,0]
	v_pk_mul_f32 v[28:29], v[28:29], v[2:3] op_sel_hi:[1,0]
	v_pk_mul_f32 v[30:31], v[30:31], v[2:3] op_sel_hi:[1,0]
	v_mov_b32_e32 v236, v0
	s_waitcnt lgkmcnt(1)
	v_mfma_f32_32x32x16_bf16 v[16:31], v[12:15], v[8:11], v[16:31]
	v_sub_f32 v8, v111, v0
	v_cvt_pk_bf16_f32 v9, v99, v100
	v_exp_f32_e32 v107, v8
	v_cvt_pk_bf16_f32 v8, v97, v98
	v_cvt_pk_bf16_f32 v10, v101, v102
	ds_read2_b64 v[12:15], v3 offset0:164 offset1:166
	v_cvt_pk_bf16_f32 v11, v103, v107
	s_waitcnt lgkmcnt(1)
	s_nop 0
	v_mfma_f32_32x32x16_bf16 v[64:79], v[4:7], v[8:11], v[64:79]
	v_add_f32 v4, v96, v97
	s_nop 0
	v_add_f32 v4, v4, v98
	s_nop 0
	v_add_f32 v4, v4, v99
	s_nop 0
	v_add_f32 v96, v4, v100
	v_sub_f32 v4, v80, v0
	s_waitcnt lgkmcnt(0)
	v_mfma_f32_32x32x16_bf16 v[48:63], v[12:15], v[8:11], v[48:63]
	v_exp_f32_e32 v80, v4
	ds_read2_b64 v[4:7], v105 offset0:196 offset1:198
	v_sub_f32 v12, v81, v0
	s_nop 0
	v_exp_f32_e32 v81, v12
	v_sub_f32 v12, v82, v0
	s_nop 0
	v_exp_f32_e32 v82, v12
	v_sub_f32 v12, v83, v0
	s_waitcnt lgkmcnt(0)
	v_mfma_f32_32x32x16_bf16 v[32:47], v[4:7], v[8:11], v[32:47]
	v_exp_f32_e32 v83, v12
	ds_read2_b64 v[12:15], v106 offset0:228 offset1:230
	v_sub_f32 v4, v84, v0
	s_nop 0
	v_exp_f32_e32 v84, v4
	v_sub_f32 v4, v85, v0
	s_nop 0
	v_exp_f32_e32 v85, v4
	v_sub_f32 v4, v86, v0
	s_waitcnt lgkmcnt(0)
	v_mfma_f32_32x32x16_bf16 v[16:31], v[12:15], v[8:11], v[16:31]
	v_exp_f32_e32 v86, v4
	ds_read2_b64 v[4:7], v104 offset0:136 offset1:138
	v_sub_f32 v8, v87, v0
	ds_read2_b64 v[12:15], v3 offset0:168 offset1:170
	v_exp_f32_e32 v87, v8
	v_cvt_pk_bf16_f32 v8, v80, v81
	v_cvt_pk_bf16_f32 v9, v82, v83
	v_cvt_pk_bf16_f32 v10, v84, v85
	v_cvt_pk_bf16_f32 v11, v86, v87
	s_waitcnt lgkmcnt(1)
	s_nop 0
	v_mfma_f32_32x32x16_bf16 v[64:79], v[4:7], v[8:11], v[64:79]
	v_add_f32 v4, v96, v101
	s_nop 0
	v_add_f32 v4, v4, v102
	s_nop 0
	v_add_f32 v4, v4, v103
	s_nop 0
	v_add_f32 v96, v4, v107
	v_sub_f32 v4, v88, v0
	s_waitcnt lgkmcnt(0)
	v_mfma_f32_32x32x16_bf16 v[48:63], v[12:15], v[8:11], v[48:63]
	v_exp_f32_e32 v88, v4
	ds_read2_b64 v[4:7], v105 offset0:200 offset1:202
	v_sub_f32 v12, v89, v0
	s_nop 0
	v_exp_f32_e32 v89, v12
	v_sub_f32 v12, v90, v0
	s_nop 0
	v_exp_f32_e32 v90, v12
	v_sub_f32 v12, v91, v0
	s_waitcnt lgkmcnt(0)
	v_mfma_f32_32x32x16_bf16 v[32:47], v[4:7], v[8:11], v[32:47]
	v_exp_f32_e32 v91, v12
	ds_read2_b64 v[12:15], v106 offset0:232 offset1:234
	v_sub_f32 v4, v92, v0
	s_nop 0
	v_exp_f32_e32 v92, v4
	v_sub_f32 v4, v93, v0
	s_nop 0
	v_exp_f32_e32 v93, v4
	v_sub_f32 v4, v94, v0
	s_waitcnt lgkmcnt(0)
	v_mfma_f32_32x32x16_bf16 v[16:31], v[12:15], v[8:11], v[16:31]
	v_exp_f32_e32 v94, v4
	ds_read2_b64 v[4:7], v104 offset0:140 offset1:142
	ds_read2_b64 v[12:15], v3 offset0:172 offset1:174
	v_sub_f32 v8, v95, v0
	v_cvt_pk_bf16_f32 v9, v90, v91
	v_exp_f32_e32 v95, v8
	v_cvt_pk_bf16_f32 v8, v88, v89
	v_cvt_pk_bf16_f32 v10, v92, v93
	v_add_f32 v3, v96, v80
	v_cvt_pk_bf16_f32 v11, v94, v95
	v_add_f32 v3, v3, v81
	s_nop 0
	v_add_f32 v3, v3, v82
	s_waitcnt lgkmcnt(1)
	v_mfma_f32_32x32x16_bf16 v[64:79], v[4:7], v[8:11], v[64:79]
	ds_read2_b64 v[4:7], v105 offset0:204 offset1:206
	v_add_f32 v3, v3, v83
	s_nop 0
	v_add_f32 v3, v3, v84
	s_nop 0
	v_add_f32 v3, v3, v85
	s_waitcnt lgkmcnt(1)
	v_mfma_f32_32x32x16_bf16 v[48:63], v[12:15], v[8:11], v[48:63]
	ds_read2_b64 v[12:15], v106 offset0:236 offset1:238
	v_add_f32 v3, v3, v86
	s_nop 0
	v_add_f32 v3, v3, v87
	s_nop 0
	v_add_f32 v3, v3, v88
	s_nop 0
	v_add_f32 v3, v3, v89
	s_waitcnt lgkmcnt(1)
	v_mfma_f32_32x32x16_bf16 v[32:47], v[4:7], v[8:11], v[32:47]
	v_add_f32 v3, v3, v90
	s_nop 0
	v_add_f32 v3, v3, v91
	s_nop 0
	v_add_f32 v3, v3, v92
	s_nop 0
	v_add_f32 v3, v3, v93
	s_waitcnt lgkmcnt(0)
	v_mfma_f32_32x32x16_bf16 v[16:31], v[12:15], v[8:11], v[16:31]
	v_add_f32 v3, v3, v94
	s_nop 0
	v_add_f32 v3, v3, v95
	s_nop 0
	v_fmac_f32_e32 v3, v246, v2
	v_mov_b32_e32 v246, v3
	s_branch .LBB0_1202
